# v47 without the barrier #3 x_sample touch (touch pruning)
# baseline (speedup 1.0000x reference)
.LBB0_487:
	v_readlane_b32 s72, v251, 2
	v_readlane_b32 s73, v251, 3
	s_cmp_lt_i32 s73, 4
	v_readlane_b32 s68, v250, 14
	v_readlane_b32 s74, v251, 4
	v_readlane_b32 s75, v251, 5
	s_cbranch_scc1 .LBB0_541
	s_waitcnt vmcnt(0)
	s_barrier
	v_readfirstlane_b32 s1, v0
	s_cmp_lt_u32 s1, 64
	s_cbranch_scc1 .Lmy_touchw_skip
	v_readlane_b32 s98, v251, 20
	v_readlane_b32 s99, v251, 21
	s_mul_i32 s0, s70, 0xa000
	s_add_u32 s0, s0, 0x800000
	s_add_u32 s98, s98, s0
	s_addc_u32 s99, s99, 0
	v_add_u32_e32 v252, 0xffffffc0, v0
	v_lshlrev_b32_e32 v252, 6, v252
	s_nop 1
	global_load_dword v255, v252, s[98:99]
	v_add_u32_e32 v253, 0x7000, v252
	global_load_dword v255, v253, s[98:99]
.Lmy_touchw_skip:
	s_mov_b64 s[2:3], exec
	v_readlane_b32 s0, v251, 41
	v_readlane_b32 s1, v251, 42
	s_and_b64 s[0:1], s[2:3], s[0:1]
	s_mov_b64 exec, s[0:1]
	s_cbranch_execz .LBB0_540
	s_add_i32 s0, 0, 0x22820
	v_mov_b32_e32 v2, s0
	s_waitcnt vmcnt(0) expcnt(0) lgkmcnt(0)
	ds_read_b32 v4, v2
	s_add_i32 s0, 0, 0x22824
	v_mov_b32_e32 v2, s0
	ds_read_b32 v2, v2
	s_waitcnt lgkmcnt(1)
	v_cmp_ne_u32_e32 vcc, 0, v4
	s_cbranch_vccnz .LBB0_504
	v_readlane_b32 s4, v251, 0
	v_readlane_b32 s5, v251, 1
	v_readlane_b32 s10, v251, 38
	s_load_dwordx2 s[0:1], s[4:5], 0x4
	v_readlane_b32 s11, v251, 39
	s_add_u32 s4, s10, 0x1000
	s_addc_u32 s5, s11, 0
	s_add_u32 s6, s10, 0x1100
	s_addc_u32 s7, s11, 0
	s_add_u32 s8, s10, 0x1200
	s_addc_u32 s9, s11, 0
	s_waitcnt lgkmcnt(0)
	s_mul_i32 s0, s0, s71
	s_add_u32 s10, s10, 0x1300
	s_mul_i32 s0, s0, s1
	s_addc_u32 s11, s11, 0
	s_mov_b32 s1, 1
	v_mov_b32_e32 v18, 0
	s_branch .LBB0_492
